# v18 with the gate-up start stagger step shortened to s_sleep 25 (~0.8us per group)
# baseline (speedup 1.0000x reference)
; __global__ void __launch_bounds__(512, 2) mega(Params p) {
;     ...
;                 } else if (ph == 4 && (PHM & 16)) {
;                     pg8::EpiGateUp E{SS2, ACT}; run_gemm(lds, XB, (const bf16_t*)(wl + WL_GU), Mg, NGU, DM, E);
.Lgu_stag:
	s_sleep 25
	s_add_i32 s52, s52, -1
	s_cmp_lg_u32 s52, 0
	s_cbranch_scc1 .Lgu_stag
